# ssd-packed-transpose-writes
# speedup vs baseline: 1.0276x; 1.0010x over previous
; #define LAS __attribute__((address_space(3)))
; __device__ __forceinline__ bf16_t f2bf(float f) { return (bf16_t)(cvt_pk_bf16(f, 0.f) & 0xffffu); }
; __device__ __forceinline__ float bflo(unsigned w) { return __uint_as_float(w << 16); }
; __device__ __forceinline__ float bfhi(unsigned w) { return __uint_as_float(w & 0xffff0000u); }
; __device__ __forceinline__ void ssd_item(const Params& p, LAS unsigned char* lds, int b, int head, bool sample) {
;     ...
;             { const int tk = 16 * (wave & 3) + (lane >> 2), cgx = 4 * (wave >> 2) + (lane & 3);
;               const u32x4 xv = P.xv; const float wt = __shfl(wl, tk);
;               *(LAS u32x4*)(lds + SSD_XTM + tk * P72 + 16 * cgx) = xv;
; #pragma unroll
;               for (int e = 0; e < 8; ++e) {
;                   const unsigned wd = xv[e >> 1]; const float xf = (e & 1) ? bfhi(wd) : bflo(wd);
;                   *(LAS bf16_t*)(lds + SSD_XT + (8 * cgx + e) * P72 + tk * 2) = (bf16_t)((e & 1) ? (wd >> 16) : (wd & 0xffffu));
;                   *(LAS bf16_t*)(lds + SSD_XTS + (8 * cgx + e) * P72 + tk * 2) = f2bf(xf * wt);
;               } }
; #pragma unroll
;             for (int i = 0; i < 2; ++i) {
;                 const int id = wave + 8 * i, tk = 16 * (id & 3) + (lane >> 2), cgb = 4 * (id >> 2) + (lane & 3);
;                 const u32x4 bv = P.bv[i];
;                 *(LAS u32x4*)(lds + SSD_BM + tk * P136 + 16 * cgb) = bv;
; #pragma unroll
;                 for (int e = 0; e < 8; ++e) { const unsigned wd = bv[e >> 1]; *(LAS bf16_t*)(lds + SSD_BT + (8 * cgb + e) * P72 + tk * 2) = (bf16_t)((e & 1) ? (wd >> 16) : (wd & 0xffffu)); }
;                 *(LAS u32x4*)(lds + SSD_CM + tk * P136 + 16 * cgb) = P.cv[i];
;             }
;         }
;         const u32x2 zq0 = P.zv[0], zq1 = P.zv[1];
;         if (c + 1 < nchunks) ssd_prefetch(P, XBCC, Z, DT, tok0 + 64, nvalid, head, grp, wave, lane, ti, tj0, fr, fq);
.LBB0_1251:
	s_waitcnt lgkmcnt(0)
	v_sub_f32_e32 v2, v166, v2
	v_mul_f32_e32 v2, 0x3fb8aa3b, v2
	v_exp_f32_e32 v2, v2
	s_mov_b32 s98, 0x5040100
	s_mov_b32 s99, 0x7060302
	s_mov_b32 s100, 0xf0f0f0f0
	s_mov_b32 s101, 0xf0f0f0f0
	v_add_u32_e32 v40, v83, v126
	ds_write_b128 v146, v[20:23]
	v_mul_f32_e32 v2, v1, v2
	ds_bpermute_b32 v2, v79, v2
	v_mov_b32_e32 v177, 0x23e
	s_add_i32 s44, s44, 1
	s_cmp_ge_u32 s44, s58
	v_cndmask_b32_e64 v177, 0, v177, s[100:101]
	v_mov_b32_e32 v101, v99
	v_add_u32_e32 v176, v40, v177
	v_mov_b32_e32 v172, v20
	v_mov_b32_e32 v173, v21
	v_mov_b32_e32 v174, v22
	v_mov_b32_e32 v175, v23
	v_mov_b32_dpp v172, v22 row_shr:4 row_mask:0xf bank_mask:0xa
	v_mov_b32_dpp v173, v23 row_shr:4 row_mask:0xf bank_mask:0xa
	v_mov_b32_dpp v174, v20 row_shl:4 row_mask:0xf bank_mask:0x5
	v_mov_b32_dpp v175, v21 row_shl:4 row_mask:0xf bank_mask:0x5
	v_perm_b32 v178, v174, v172, s98
	v_perm_b32 v179, v174, v172, s99
	v_perm_b32 v180, v175, v173, s98
	v_perm_b32 v181, v175, v173, s99
	ds_write_b32 v176, v178 offset:53248
	ds_write_b32 v176, v179 offset:53392
	ds_write_b32 v176, v180 offset:53536
	ds_write_b32 v176, v181 offset:53680
	s_waitcnt lgkmcnt(4)
	v_lshlrev_b32_e32 v182, 16, v20
	v_and_b32_e32 v183, 0xffff0000, v20
	v_lshlrev_b32_e32 v184, 16, v21
	v_and_b32_e32 v185, 0xffff0000, v21
	v_lshlrev_b32_e32 v186, 16, v22
	v_and_b32_e32 v187, 0xffff0000, v22
	v_lshlrev_b32_e32 v188, 16, v23
	v_and_b32_e32 v189, 0xffff0000, v23
	v_mul_f32_e32 v182, v182, v2
	v_mul_f32_e32 v183, v183, v2
	v_mul_f32_e32 v184, v184, v2
	v_mul_f32_e32 v185, v185, v2
	v_mul_f32_e32 v186, v186, v2
	v_mul_f32_e32 v187, v187, v2
	v_mul_f32_e32 v188, v188, v2
	v_mul_f32_e32 v189, v189, v2
	v_cvt_pk_bf16_f32 v182, v182, v183
	v_cvt_pk_bf16_f32 v184, v184, v185
	v_cvt_pk_bf16_f32 v186, v186, v187
	v_cvt_pk_bf16_f32 v188, v188, v189
	v_mov_b32_e32 v190, v182
	v_mov_b32_e32 v191, v184
	v_mov_b32_e32 v192, v186
	v_mov_b32_e32 v193, v188
	v_mov_b32_dpp v190, v186 row_shr:4 row_mask:0xf bank_mask:0xa
	v_mov_b32_dpp v191, v188 row_shr:4 row_mask:0xf bank_mask:0xa
	v_mov_b32_dpp v192, v182 row_shl:4 row_mask:0xf bank_mask:0x5
	v_mov_b32_dpp v193, v184 row_shl:4 row_mask:0xf bank_mask:0x5
	v_perm_b32 v194, v192, v190, s98
	v_perm_b32 v195, v192, v190, s99
	v_perm_b32 v196, v193, v191, s98
	v_perm_b32 v197, v193, v191, s99
	ds_write_b32 v176, v194 offset:62464
	ds_write_b32 v176, v195 offset:62608
	ds_write_b32 v176, v196 offset:62752
	ds_write_b32 v176, v197 offset:62896
	v_add_u32_e32 v2, v109, v81
	ds_write_b128 v2, v[24:27] offset:17408
	v_add3_u32 v198, v110, v126, v177
	v_mov_b32_e32 v199, v24
	v_mov_b32_e32 v200, v25
	v_mov_b32_e32 v201, v26
	v_mov_b32_e32 v202, v27
	v_mov_b32_dpp v199, v26 row_shr:4 row_mask:0xf bank_mask:0xa
	v_mov_b32_dpp v200, v27 row_shr:4 row_mask:0xf bank_mask:0xa
	v_mov_b32_dpp v201, v24 row_shl:4 row_mask:0xf bank_mask:0x5
	v_mov_b32_dpp v202, v25 row_shl:4 row_mask:0xf bank_mask:0x5
	v_perm_b32 v203, v201, v199, s98
	v_perm_b32 v204, v201, v199, s99
	v_perm_b32 v205, v202, v200, s98
	v_perm_b32 v206, v202, v200, s99
	ds_write_b32 v198, v203 offset:34816
	ds_write_b32 v198, v204 offset:34960
	ds_write_b32 v198, v205 offset:35104
	ds_write_b32 v198, v206 offset:35248
	v_add_u32_e32 v2, v111, v81
	ds_write_b128 v2, v[28:31]
	v_add_u32_e32 v2, v109, v127
	ds_write_b128 v2, v[32:35] offset:17408
	v_add_u32_e32 v207, v147, v177
	v_mov_b32_e32 v208, v32
	v_mov_b32_e32 v209, v33
	v_mov_b32_e32 v210, v34
	v_mov_b32_e32 v211, v35
	v_mov_b32_dpp v208, v34 row_shr:4 row_mask:0xf bank_mask:0xa
	v_mov_b32_dpp v209, v35 row_shr:4 row_mask:0xf bank_mask:0xa
	v_mov_b32_dpp v210, v32 row_shl:4 row_mask:0xf bank_mask:0x5
	v_mov_b32_dpp v211, v33 row_shl:4 row_mask:0xf bank_mask:0x5
	v_perm_b32 v212, v210, v208, s98
	v_perm_b32 v213, v210, v208, s99
	v_perm_b32 v214, v211, v209, s98
	v_perm_b32 v215, v211, v209, s99
	ds_write_b32 v207, v212 offset:34816
	ds_write_b32 v207, v213 offset:34960
	ds_write_b32 v207, v214 offset:35104
	ds_write_b32 v207, v215 offset:35248
	v_add_u32_e32 v2, v111, v127
	ds_write_b128 v2, v[36:39]
	v_mov_b32_e32 v3, v103
	v_mov_b32_e32 v2, v102
	v_mov_b32_e32 v100, v98
	s_cbranch_scc1 .LBB0_1263
	v_mov_b32_e32 v24, 0
	v_mov_b32_e32 v25, v0
	v_mov_b32_e32 v26, v0
	v_mov_b32_e32 v27, v0
	v_mov_b64_e32 v[20:21], v[24:25]
	v_mov_b64_e32 v[22:23], v[26:27]
	s_and_saveexec_b64 s[52:53], s[6:7]
	s_cbranch_execz .LBB0_1254
	v_lshl_add_u64 v[2:3], s[92:93], 0, v[88:89]
	global_load_dwordx4 v[20:23], v[2:3], off
